# s_setprio 0 moved behind the MFMA-closing barrier (plus setprio 1 before the opening barrier, fillers stripped), on top of v45
# baseline (speedup 1.0000x reference)
.LBB0_233:
	ds_read_b128 v[130:133], v213
	ds_read_b128 v[134:137], v214
	ds_read_b128 v[138:141], v215
	ds_read_b128 v[142:145], v216
	ds_read_b128 v[146:149], v217
	ds_read_b128 v[150:153], v218
	ds_read_b128 v[154:157], v219
	ds_read_b128 v[158:161], v220
	s_add_i32 s4, s33, 0xffffe080
	s_cmp_eq_u32 s58, 12
	s_cselect_b32 s61, s18, s4
	s_cselect_b32 s60, s19, s57
	s_add_i32 s59, s61, 0x80
	s_mov_b32 s4, s70
	s_mov_b32 m0, s38
	ds_read_b128 v[162:165], v221
	ds_read_b128 v[166:169], v221 offset:2048
	ds_read_b128 v[170:173], v222
	ds_read_b128 v[174:177], v222 offset:2048
	ds_read_b128 v[178:181], v221 offset:4096
	ds_read_b128 v[182:185], v221 offset:6144
	ds_read_b128 v[186:189], v222 offset:4096
	ds_read_b128 v[190:193], v222 offset:6144
	buffer_load_dwordx4 v207, s[4:7], s33 offen lds
	s_mov_b32 m0, s41
	s_nop 0
	buffer_load_dwordx4 v209, s[4:7], s33 offen lds
	s_waitcnt vmcnt(8)
	s_waitcnt lgkmcnt(0)
	s_setprio 1
	s_barrier
	v_mfma_f32_16x16x32_bf16 v[114:117], v[130:133], v[162:165], v[114:117]
	v_mfma_f32_16x16x32_bf16 v[110:113], v[138:141], v[162:165], v[110:113]
	v_mfma_f32_16x16x32_bf16 v[106:109], v[130:133], v[166:169], v[106:109]
	v_mfma_f32_16x16x32_bf16 v[102:105], v[138:141], v[166:169], v[102:105]
	v_mfma_f32_16x16x32_bf16 v[98:101], v[130:133], v[178:181], v[98:101]
	v_mfma_f32_16x16x32_bf16 v[94:97], v[138:141], v[178:181], v[94:97]
	v_mfma_f32_16x16x32_bf16 v[90:93], v[130:133], v[182:185], v[90:93]
	v_mfma_f32_16x16x32_bf16 v[86:89], v[138:141], v[182:185], v[86:89]
	v_mfma_f32_16x16x32_bf16 v[114:117], v[134:137], v[170:173], v[114:117]
	v_mfma_f32_16x16x32_bf16 v[110:113], v[142:145], v[170:173], v[110:113]
	v_mfma_f32_16x16x32_bf16 v[106:109], v[134:137], v[174:177], v[106:109]
	v_mfma_f32_16x16x32_bf16 v[102:105], v[142:145], v[174:177], v[102:105]
	v_mfma_f32_16x16x32_bf16 v[98:101], v[134:137], v[186:189], v[98:101]
	v_mfma_f32_16x16x32_bf16 v[94:97], v[142:145], v[186:189], v[94:97]
	v_mfma_f32_16x16x32_bf16 v[90:93], v[134:137], v[190:193], v[90:93]
	v_mfma_f32_16x16x32_bf16 v[86:89], v[142:145], v[190:193], v[86:89]
	v_mfma_f32_16x16x32_bf16 v[82:85], v[146:149], v[162:165], v[82:85]
	v_mfma_f32_16x16x32_bf16 v[74:77], v[154:157], v[162:165], v[74:77]
	v_mfma_f32_16x16x32_bf16 v[70:73], v[146:149], v[166:169], v[70:73]
	v_mfma_f32_16x16x32_bf16 v[66:69], v[154:157], v[166:169], v[66:69]
	v_mfma_f32_16x16x32_bf16 v[62:65], v[146:149], v[178:181], v[62:65]
	v_mfma_f32_16x16x32_bf16 v[58:61], v[154:157], v[178:181], v[58:61]
	v_mfma_f32_16x16x32_bf16 v[54:57], v[146:149], v[182:185], v[54:57]
	v_mfma_f32_16x16x32_bf16 v[50:53], v[154:157], v[182:185], v[50:53]
	v_mfma_f32_16x16x32_bf16 v[82:85], v[150:153], v[170:173], v[82:85]
	v_mfma_f32_16x16x32_bf16 v[74:77], v[158:161], v[170:173], v[74:77]
	v_mfma_f32_16x16x32_bf16 v[70:73], v[150:153], v[174:177], v[70:73]
	v_mfma_f32_16x16x32_bf16 v[66:69], v[158:161], v[174:177], v[66:69]
	v_mfma_f32_16x16x32_bf16 v[62:65], v[150:153], v[186:189], v[62:65]
	v_mfma_f32_16x16x32_bf16 v[58:61], v[158:161], v[186:189], v[58:61]
	v_mfma_f32_16x16x32_bf16 v[54:57], v[150:153], v[190:193], v[54:57]
	v_mfma_f32_16x16x32_bf16 v[50:53], v[158:161], v[190:193], v[50:53]
	s_barrier
	s_setprio 0
	s_mov_b32 m0, s21
	ds_read_b128 v[162:165], v221 offset:16384
	ds_read_b128 v[166:169], v221 offset:18432
	ds_read_b128 v[170:173], v222 offset:16384
	ds_read_b128 v[174:177], v222 offset:18432
	ds_read_b128 v[178:181], v221 offset:20480
	ds_read_b128 v[182:185], v221 offset:22528
	ds_read_b128 v[186:189], v222 offset:20480
	ds_read_b128 v[190:193], v222 offset:22528
	buffer_load_dwordx4 v208, s[4:7], s60 offen lds
	s_mov_b32 m0, s22
	s_add_i32 s62, s60, 0x40000
	buffer_load_dwordx4 v210, s[4:7], s60 offen lds
	s_mov_b32 m0, s23
	s_nop 0
	buffer_load_dwordx4 v208, s[4:7], s62 offen lds
	s_mov_b32 m0, s24
	s_nop 0
	buffer_load_dwordx4 v210, s[4:7], s62 offen lds
	s_mov_b32 m0, s20
	s_nop 0
	buffer_load_dwordx4 v207, s[4:7], s61 offen lds
	s_mov_b32 m0, s25
	s_nop 0
	buffer_load_dwordx4 v209, s[4:7], s61 offen lds
	s_waitcnt vmcnt(8)
	s_waitcnt lgkmcnt(0)
	s_setprio 1
	s_barrier
	v_mfma_f32_16x16x32_bf16 v[78:81], v[130:133], v[162:165], v[78:81]
	v_mfma_f32_16x16x32_bf16 v[46:49], v[138:141], v[162:165], v[46:49]
	v_mfma_f32_16x16x32_bf16 v[42:45], v[130:133], v[166:169], v[42:45]
	v_mfma_f32_16x16x32_bf16 v[38:41], v[138:141], v[166:169], v[38:41]
	v_mfma_f32_16x16x32_bf16 v[34:37], v[130:133], v[178:181], v[34:37]
	v_mfma_f32_16x16x32_bf16 v[30:33], v[138:141], v[178:181], v[30:33]
	v_mfma_f32_16x16x32_bf16 v[26:29], v[130:133], v[182:185], v[26:29]
	v_mfma_f32_16x16x32_bf16 v[22:25], v[138:141], v[182:185], v[22:25]
	v_mfma_f32_16x16x32_bf16 v[78:81], v[134:137], v[170:173], v[78:81]
	v_mfma_f32_16x16x32_bf16 v[46:49], v[142:145], v[170:173], v[46:49]
	v_mfma_f32_16x16x32_bf16 v[42:45], v[134:137], v[174:177], v[42:45]
	v_mfma_f32_16x16x32_bf16 v[38:41], v[142:145], v[174:177], v[38:41]
	v_mfma_f32_16x16x32_bf16 v[34:37], v[134:137], v[186:189], v[34:37]
	v_mfma_f32_16x16x32_bf16 v[30:33], v[142:145], v[186:189], v[30:33]
	v_mfma_f32_16x16x32_bf16 v[26:29], v[134:137], v[190:193], v[26:29]
	v_mfma_f32_16x16x32_bf16 v[22:25], v[142:145], v[190:193], v[22:25]
	v_mfma_f32_16x16x32_bf16 v[18:21], v[146:149], v[162:165], v[18:21]
	v_mfma_f32_16x16x32_bf16 v[14:17], v[154:157], v[162:165], v[14:17]
	v_mfma_f32_16x16x32_bf16 v[10:13], v[146:149], v[166:169], v[10:13]
	v_mfma_f32_16x16x32_bf16 v[6:9], v[154:157], v[166:169], v[6:9]
	v_mfma_f32_16x16x32_bf16 v[2:5], v[146:149], v[178:181], v[2:5]
	v_mfma_f32_16x16x32_bf16 v[126:129], v[154:157], v[178:181], v[126:129]
	v_mfma_f32_16x16x32_bf16 v[122:125], v[146:149], v[182:185], v[122:125]
	v_mfma_f32_16x16x32_bf16 v[118:121], v[154:157], v[182:185], v[118:121]
	v_mfma_f32_16x16x32_bf16 v[18:21], v[150:153], v[170:173], v[18:21]
	v_mfma_f32_16x16x32_bf16 v[14:17], v[158:161], v[170:173], v[14:17]
	v_mfma_f32_16x16x32_bf16 v[10:13], v[150:153], v[174:177], v[10:13]
	v_mfma_f32_16x16x32_bf16 v[6:9], v[158:161], v[174:177], v[6:9]
	v_mfma_f32_16x16x32_bf16 v[2:5], v[150:153], v[186:189], v[2:5]
	v_mfma_f32_16x16x32_bf16 v[126:129], v[158:161], v[186:189], v[126:129]
	v_mfma_f32_16x16x32_bf16 v[122:125], v[150:153], v[190:193], v[122:125]
	v_mfma_f32_16x16x32_bf16 v[118:121], v[158:161], v[190:193], v[118:121]
	s_barrier
	s_setprio 0
	ds_read_b128 v[130:133], v194
	ds_read_b128 v[134:137], v224
	ds_read_b128 v[138:141], v225
	ds_read_b128 v[142:145], v228
	ds_read_b128 v[146:149], v229
	ds_read_b128 v[150:153], v230
	ds_read_b128 v[154:157], v231
	ds_read_b128 v[158:161], v233
	s_addk_i32 s61, 0x2000
	s_mov_b32 m0, s26
	ds_read_b128 v[162:165], v221 offset:32768
	ds_read_b128 v[166:169], v221 offset:34816
	ds_read_b128 v[170:173], v222 offset:32768
	ds_read_b128 v[174:177], v222 offset:34816
	ds_read_b128 v[178:181], v221 offset:36864
	ds_read_b128 v[182:185], v221 offset:38912
	ds_read_b128 v[186:189], v222 offset:36864
	ds_read_b128 v[190:193], v222 offset:38912
	buffer_load_dwordx4 v207, s[4:7], s61 offen lds
	s_mov_b32 m0, s27
	s_nop 0
	buffer_load_dwordx4 v209, s[4:7], s61 offen lds
	s_waitcnt vmcnt(8)
	s_waitcnt lgkmcnt(0)
	s_setprio 1
	s_barrier
	v_mfma_f32_16x16x32_bf16 v[114:117], v[130:133], v[162:165], v[114:117]
	v_mfma_f32_16x16x32_bf16 v[110:113], v[138:141], v[162:165], v[110:113]
	v_mfma_f32_16x16x32_bf16 v[106:109], v[130:133], v[166:169], v[106:109]
	v_mfma_f32_16x16x32_bf16 v[102:105], v[138:141], v[166:169], v[102:105]
	v_mfma_f32_16x16x32_bf16 v[98:101], v[130:133], v[178:181], v[98:101]
	v_mfma_f32_16x16x32_bf16 v[94:97], v[138:141], v[178:181], v[94:97]
	v_mfma_f32_16x16x32_bf16 v[90:93], v[130:133], v[182:185], v[90:93]
	v_mfma_f32_16x16x32_bf16 v[86:89], v[138:141], v[182:185], v[86:89]
	v_mfma_f32_16x16x32_bf16 v[114:117], v[134:137], v[170:173], v[114:117]
	v_mfma_f32_16x16x32_bf16 v[110:113], v[142:145], v[170:173], v[110:113]
	v_mfma_f32_16x16x32_bf16 v[106:109], v[134:137], v[174:177], v[106:109]
	v_mfma_f32_16x16x32_bf16 v[102:105], v[142:145], v[174:177], v[102:105]
	v_mfma_f32_16x16x32_bf16 v[98:101], v[134:137], v[186:189], v[98:101]
	v_mfma_f32_16x16x32_bf16 v[94:97], v[142:145], v[186:189], v[94:97]
	v_mfma_f32_16x16x32_bf16 v[90:93], v[134:137], v[190:193], v[90:93]
	v_mfma_f32_16x16x32_bf16 v[86:89], v[142:145], v[190:193], v[86:89]
	v_mfma_f32_16x16x32_bf16 v[82:85], v[146:149], v[162:165], v[82:85]
	v_mfma_f32_16x16x32_bf16 v[74:77], v[154:157], v[162:165], v[74:77]
	v_mfma_f32_16x16x32_bf16 v[70:73], v[146:149], v[166:169], v[70:73]
	v_mfma_f32_16x16x32_bf16 v[66:69], v[154:157], v[166:169], v[66:69]
	v_mfma_f32_16x16x32_bf16 v[62:65], v[146:149], v[178:181], v[62:65]
	v_mfma_f32_16x16x32_bf16 v[58:61], v[154:157], v[178:181], v[58:61]
	v_mfma_f32_16x16x32_bf16 v[54:57], v[146:149], v[182:185], v[54:57]
	v_mfma_f32_16x16x32_bf16 v[50:53], v[154:157], v[182:185], v[50:53]
	v_mfma_f32_16x16x32_bf16 v[82:85], v[150:153], v[170:173], v[82:85]
	v_mfma_f32_16x16x32_bf16 v[74:77], v[158:161], v[170:173], v[74:77]
	v_mfma_f32_16x16x32_bf16 v[70:73], v[150:153], v[174:177], v[70:73]
	v_mfma_f32_16x16x32_bf16 v[66:69], v[158:161], v[174:177], v[66:69]
	v_mfma_f32_16x16x32_bf16 v[62:65], v[150:153], v[186:189], v[62:65]
	v_mfma_f32_16x16x32_bf16 v[58:61], v[158:161], v[186:189], v[58:61]
	v_mfma_f32_16x16x32_bf16 v[54:57], v[150:153], v[190:193], v[54:57]
	v_mfma_f32_16x16x32_bf16 v[50:53], v[158:161], v[190:193], v[50:53]
	s_barrier
	s_setprio 0
	s_mov_b32 m0, s29
	s_add_i32 s61, s60, 0x80
	ds_read_b128 v[162:165], v221 offset:49152
	ds_read_b128 v[166:169], v221 offset:51200
	ds_read_b128 v[170:173], v222 offset:49152
	ds_read_b128 v[174:177], v222 offset:51200
	ds_read_b128 v[178:181], v221 offset:53248
	ds_read_b128 v[182:185], v221 offset:55296
	ds_read_b128 v[186:189], v222 offset:53248
	ds_read_b128 v[190:193], v222 offset:55296
	buffer_load_dwordx4 v208, s[4:7], s61 offen lds
	s_mov_b32 m0, s30
	s_add_i32 s60, s60, 0x40080
	buffer_load_dwordx4 v210, s[4:7], s61 offen lds
	s_mov_b32 m0, s35
	s_nop 0
	buffer_load_dwordx4 v208, s[4:7], s60 offen lds
	s_mov_b32 m0, s36
	s_nop 0
	buffer_load_dwordx4 v210, s[4:7], s60 offen lds
	s_mov_b32 m0, s31
	s_nop 0
	buffer_load_dwordx4 v207, s[4:7], s59 offen lds
	s_mov_b32 m0, s34
	s_nop 0
	buffer_load_dwordx4 v209, s[4:7], s59 offen lds
	s_waitcnt vmcnt(8)
	s_waitcnt lgkmcnt(0)
	s_setprio 1
	s_barrier
	v_mfma_f32_16x16x32_bf16 v[78:81], v[130:133], v[162:165], v[78:81]
	v_mfma_f32_16x16x32_bf16 v[46:49], v[138:141], v[162:165], v[46:49]
	v_mfma_f32_16x16x32_bf16 v[42:45], v[130:133], v[166:169], v[42:45]
	v_mfma_f32_16x16x32_bf16 v[38:41], v[138:141], v[166:169], v[38:41]
	v_mfma_f32_16x16x32_bf16 v[34:37], v[130:133], v[178:181], v[34:37]
	v_mfma_f32_16x16x32_bf16 v[30:33], v[138:141], v[178:181], v[30:33]
	v_mfma_f32_16x16x32_bf16 v[26:29], v[130:133], v[182:185], v[26:29]
	v_mfma_f32_16x16x32_bf16 v[22:25], v[138:141], v[182:185], v[22:25]
	v_mfma_f32_16x16x32_bf16 v[78:81], v[134:137], v[170:173], v[78:81]
	v_mfma_f32_16x16x32_bf16 v[46:49], v[142:145], v[170:173], v[46:49]
	v_mfma_f32_16x16x32_bf16 v[42:45], v[134:137], v[174:177], v[42:45]
	v_mfma_f32_16x16x32_bf16 v[38:41], v[142:145], v[174:177], v[38:41]
	v_mfma_f32_16x16x32_bf16 v[34:37], v[134:137], v[186:189], v[34:37]
	v_mfma_f32_16x16x32_bf16 v[30:33], v[142:145], v[186:189], v[30:33]
	v_mfma_f32_16x16x32_bf16 v[26:29], v[134:137], v[190:193], v[26:29]
	v_mfma_f32_16x16x32_bf16 v[22:25], v[142:145], v[190:193], v[22:25]
	v_mfma_f32_16x16x32_bf16 v[18:21], v[146:149], v[162:165], v[18:21]
	v_mfma_f32_16x16x32_bf16 v[14:17], v[154:157], v[162:165], v[14:17]
	v_mfma_f32_16x16x32_bf16 v[10:13], v[146:149], v[166:169], v[10:13]
	v_mfma_f32_16x16x32_bf16 v[6:9], v[154:157], v[166:169], v[6:9]
	v_mfma_f32_16x16x32_bf16 v[2:5], v[146:149], v[178:181], v[2:5]
	v_mfma_f32_16x16x32_bf16 v[126:129], v[154:157], v[178:181], v[126:129]
	v_mfma_f32_16x16x32_bf16 v[122:125], v[146:149], v[182:185], v[122:125]
	v_mfma_f32_16x16x32_bf16 v[118:121], v[154:157], v[182:185], v[118:121]
	v_mfma_f32_16x16x32_bf16 v[18:21], v[150:153], v[170:173], v[18:21]
	v_mfma_f32_16x16x32_bf16 v[14:17], v[158:161], v[170:173], v[14:17]
	v_mfma_f32_16x16x32_bf16 v[10:13], v[150:153], v[174:177], v[10:13]
	v_mfma_f32_16x16x32_bf16 v[6:9], v[158:161], v[174:177], v[6:9]
	v_mfma_f32_16x16x32_bf16 v[2:5], v[150:153], v[186:189], v[2:5]
	v_mfma_f32_16x16x32_bf16 v[126:129], v[158:161], v[186:189], v[126:129]
	v_mfma_f32_16x16x32_bf16 v[122:125], v[150:153], v[190:193], v[122:125]
	v_mfma_f32_16x16x32_bf16 v[118:121], v[158:161], v[190:193], v[118:121]
	s_barrier
	s_setprio 0
	s_add_i32 s58, s58, 2
	s_addk_i32 s33, 0x100
	s_addk_i32 s57, 0x100
	s_cmp_gt_u32 s58, 13
	s_cbranch_scc0 .LBB0_233
	s_and_b64 vcc, exec, s[16:17]
	s_cbranch_vccz .LBB0_236
	s_barrier

.LBB0_546:
	ds_read_b128 v[130:133], v211
	ds_read_b128 v[134:137], v212
	ds_read_b128 v[138:141], v213
	ds_read_b128 v[142:145], v214
	ds_read_b128 v[146:149], v215
	ds_read_b128 v[150:153], v216
	ds_read_b128 v[154:157], v217
	ds_read_b128 v[158:161], v218
	s_add_i32 s4, s62, 0x80
	s_cmp_eq_u32 s63, s78
	s_cselect_b32 s84, s64, s4
	s_cselect_b32 s82, s33, s59
	s_cselect_b32 s81, s65, s61
	s_cselect_b32 s80, s56, s60
	s_add_i32 s79, s84, 0x80
	s_add_i32 s83, s60, s62
	s_mov_b32 s4, s70
	s_mov_b32 m0, s43
	ds_read_b128 v[162:165], v219
	ds_read_b128 v[166:169], v219 offset:2048
	ds_read_b128 v[170:173], v220
	ds_read_b128 v[174:177], v220 offset:2048
	ds_read_b128 v[178:181], v219 offset:4096
	ds_read_b128 v[182:185], v219 offset:6144
	ds_read_b128 v[186:189], v220 offset:4096
	ds_read_b128 v[190:193], v220 offset:6144
	buffer_load_dwordx4 v194, s[4:7], s83 offen lds
	s_mov_b32 m0, s44
	s_nop 0
	buffer_load_dwordx4 v222, s[4:7], s83 offen lds
	s_waitcnt vmcnt(8)
	s_waitcnt lgkmcnt(0)
	s_setprio 1
	s_barrier
	v_mfma_f32_16x16x32_bf16 v[126:129], v[130:133], v[162:165], v[126:129]
	v_mfma_f32_16x16x32_bf16 v[122:125], v[138:141], v[162:165], v[122:125]
	v_mfma_f32_16x16x32_bf16 v[118:121], v[130:133], v[166:169], v[118:121]
	v_mfma_f32_16x16x32_bf16 v[114:117], v[138:141], v[166:169], v[114:117]
	v_mfma_f32_16x16x32_bf16 v[110:113], v[130:133], v[178:181], v[110:113]
	v_mfma_f32_16x16x32_bf16 v[106:109], v[138:141], v[178:181], v[106:109]
	v_mfma_f32_16x16x32_bf16 v[102:105], v[130:133], v[182:185], v[102:105]
	v_mfma_f32_16x16x32_bf16 v[98:101], v[138:141], v[182:185], v[98:101]
	v_mfma_f32_16x16x32_bf16 v[126:129], v[134:137], v[170:173], v[126:129]
	v_mfma_f32_16x16x32_bf16 v[122:125], v[142:145], v[170:173], v[122:125]
	v_mfma_f32_16x16x32_bf16 v[118:121], v[134:137], v[174:177], v[118:121]
	v_mfma_f32_16x16x32_bf16 v[114:117], v[142:145], v[174:177], v[114:117]
	v_mfma_f32_16x16x32_bf16 v[110:113], v[134:137], v[186:189], v[110:113]
	v_mfma_f32_16x16x32_bf16 v[106:109], v[142:145], v[186:189], v[106:109]
	v_mfma_f32_16x16x32_bf16 v[102:105], v[134:137], v[190:193], v[102:105]
	v_mfma_f32_16x16x32_bf16 v[98:101], v[142:145], v[190:193], v[98:101]
	v_mfma_f32_16x16x32_bf16 v[94:97], v[146:149], v[162:165], v[94:97]
	v_mfma_f32_16x16x32_bf16 v[90:93], v[154:157], v[162:165], v[90:93]
	v_mfma_f32_16x16x32_bf16 v[86:89], v[146:149], v[166:169], v[86:89]
	v_mfma_f32_16x16x32_bf16 v[82:85], v[154:157], v[166:169], v[82:85]
	v_mfma_f32_16x16x32_bf16 v[78:81], v[146:149], v[178:181], v[78:81]
	v_mfma_f32_16x16x32_bf16 v[74:77], v[154:157], v[178:181], v[74:77]
	v_mfma_f32_16x16x32_bf16 v[70:73], v[146:149], v[182:185], v[70:73]
	v_mfma_f32_16x16x32_bf16 v[66:69], v[154:157], v[182:185], v[66:69]
	v_mfma_f32_16x16x32_bf16 v[94:97], v[150:153], v[170:173], v[94:97]
	v_mfma_f32_16x16x32_bf16 v[90:93], v[158:161], v[170:173], v[90:93]
	v_mfma_f32_16x16x32_bf16 v[86:89], v[150:153], v[174:177], v[86:89]
	v_mfma_f32_16x16x32_bf16 v[82:85], v[158:161], v[174:177], v[82:85]
	v_mfma_f32_16x16x32_bf16 v[78:81], v[150:153], v[186:189], v[78:81]
	v_mfma_f32_16x16x32_bf16 v[74:77], v[158:161], v[186:189], v[74:77]
	v_mfma_f32_16x16x32_bf16 v[70:73], v[150:153], v[190:193], v[70:73]
	v_mfma_f32_16x16x32_bf16 v[66:69], v[158:161], v[190:193], v[66:69]
	s_barrier
	s_setprio 0
	s_cmp_eq_u32 s82, 0
	s_cselect_b64 s[82:83], -1, 0
	v_cndmask_b32_e64 v233, v200, 0, s[82:83]
	s_mov_b32 m0, s25
	v_sub_u32_e32 v233, v201, v233
	v_cndmask_b32_e64 v234, v203, 0, s[82:83]
	ds_read_b128 v[162:165], v219 offset:16384
	ds_read_b128 v[166:169], v219 offset:18432
	ds_read_b128 v[170:173], v220 offset:16384
	ds_read_b128 v[174:177], v220 offset:18432
	ds_read_b128 v[178:181], v219 offset:20480
	ds_read_b128 v[182:185], v219 offset:22528
	ds_read_b128 v[186:189], v220 offset:20480
	ds_read_b128 v[190:193], v220 offset:22528
	buffer_load_dwordx4 v233, s[4:7], s81 offen lds
	v_sub_u32_e32 v234, v204, v234
	s_mov_b32 m0, s26
	s_add_i32 s85, s81, s80
	buffer_load_dwordx4 v234, s[4:7], s81 offen lds
	s_mov_b32 m0, s27
	v_cndmask_b32_e64 v235, v205, 0, s[82:83]
	buffer_load_dwordx4 v233, s[4:7], s85 offen lds
	s_mov_b32 m0, s28
	v_sub_u32_e32 v235, v1, v235
	buffer_load_dwordx4 v234, s[4:7], s85 offen lds
	s_mov_b32 m0, s24
	v_cndmask_b32_e64 v236, v206, 0, s[82:83]
	buffer_load_dwordx4 v235, s[4:7], s84 offen lds
	v_sub_u32_e32 v236, v202, v236
	s_mov_b32 m0, s29
	s_nop 0
	buffer_load_dwordx4 v236, s[4:7], s84 offen lds
	s_waitcnt vmcnt(8)
	s_waitcnt lgkmcnt(0)
	s_setprio 1
	s_barrier
	v_mfma_f32_16x16x32_bf16 v[62:65], v[130:133], v[162:165], v[62:65]
	v_mfma_f32_16x16x32_bf16 v[58:61], v[138:141], v[162:165], v[58:61]
	v_mfma_f32_16x16x32_bf16 v[54:57], v[130:133], v[166:169], v[54:57]
	v_mfma_f32_16x16x32_bf16 v[50:53], v[138:141], v[166:169], v[50:53]
	v_mfma_f32_16x16x32_bf16 v[46:49], v[130:133], v[178:181], v[46:49]
	v_mfma_f32_16x16x32_bf16 v[42:45], v[138:141], v[178:181], v[42:45]
	v_mfma_f32_16x16x32_bf16 v[38:41], v[130:133], v[182:185], v[38:41]
	v_mfma_f32_16x16x32_bf16 v[34:37], v[138:141], v[182:185], v[34:37]
	v_mfma_f32_16x16x32_bf16 v[62:65], v[134:137], v[170:173], v[62:65]
	v_mfma_f32_16x16x32_bf16 v[58:61], v[142:145], v[170:173], v[58:61]
	v_mfma_f32_16x16x32_bf16 v[54:57], v[134:137], v[174:177], v[54:57]
	v_mfma_f32_16x16x32_bf16 v[50:53], v[142:145], v[174:177], v[50:53]
	v_mfma_f32_16x16x32_bf16 v[46:49], v[134:137], v[186:189], v[46:49]
	v_mfma_f32_16x16x32_bf16 v[42:45], v[142:145], v[186:189], v[42:45]
	v_mfma_f32_16x16x32_bf16 v[38:41], v[134:137], v[190:193], v[38:41]
	v_mfma_f32_16x16x32_bf16 v[34:37], v[142:145], v[190:193], v[34:37]
	v_mfma_f32_16x16x32_bf16 v[30:33], v[146:149], v[162:165], v[30:33]
	v_mfma_f32_16x16x32_bf16 v[26:29], v[154:157], v[162:165], v[26:29]
	v_mfma_f32_16x16x32_bf16 v[22:25], v[146:149], v[166:169], v[22:25]
	v_mfma_f32_16x16x32_bf16 v[18:21], v[154:157], v[166:169], v[18:21]
	v_mfma_f32_16x16x32_bf16 v[14:17], v[146:149], v[178:181], v[14:17]
	v_mfma_f32_16x16x32_bf16 v[10:13], v[154:157], v[178:181], v[10:13]
	v_mfma_f32_16x16x32_bf16 v[6:9], v[146:149], v[182:185], v[6:9]
	v_mfma_f32_16x16x32_bf16 v[2:5], v[154:157], v[182:185], v[2:5]
	v_mfma_f32_16x16x32_bf16 v[30:33], v[150:153], v[170:173], v[30:33]
	v_mfma_f32_16x16x32_bf16 v[26:29], v[158:161], v[170:173], v[26:29]
	v_mfma_f32_16x16x32_bf16 v[22:25], v[150:153], v[174:177], v[22:25]
	v_mfma_f32_16x16x32_bf16 v[18:21], v[158:161], v[174:177], v[18:21]
	v_mfma_f32_16x16x32_bf16 v[14:17], v[150:153], v[186:189], v[14:17]
	v_mfma_f32_16x16x32_bf16 v[10:13], v[158:161], v[186:189], v[10:13]
	v_mfma_f32_16x16x32_bf16 v[6:9], v[150:153], v[190:193], v[6:9]
	v_mfma_f32_16x16x32_bf16 v[2:5], v[158:161], v[190:193], v[2:5]
	s_barrier
	s_setprio 0
	ds_read_b128 v[130:133], v223
	ds_read_b128 v[134:137], v224
	ds_read_b128 v[138:141], v225
	ds_read_b128 v[142:145], v227
	ds_read_b128 v[146:149], v228
	ds_read_b128 v[150:153], v229
	ds_read_b128 v[154:157], v230
	ds_read_b128 v[158:161], v231
	s_add_i32 s84, s84, s80
	s_mov_b32 m0, s30
	ds_read_b128 v[162:165], v219 offset:32768
	ds_read_b128 v[166:169], v219 offset:34816
	ds_read_b128 v[170:173], v220 offset:32768
	ds_read_b128 v[174:177], v220 offset:34816
	ds_read_b128 v[178:181], v219 offset:36864
	ds_read_b128 v[182:185], v219 offset:38912
	ds_read_b128 v[186:189], v220 offset:36864
	ds_read_b128 v[190:193], v220 offset:38912
	buffer_load_dwordx4 v235, s[4:7], s84 offen lds
	s_mov_b32 m0, s31
	s_nop 0
	buffer_load_dwordx4 v236, s[4:7], s84 offen lds
	s_waitcnt vmcnt(8)
	s_waitcnt lgkmcnt(0)
	s_setprio 1
	s_barrier
	v_mfma_f32_16x16x32_bf16 v[126:129], v[130:133], v[162:165], v[126:129]
	v_mfma_f32_16x16x32_bf16 v[122:125], v[138:141], v[162:165], v[122:125]
	v_mfma_f32_16x16x32_bf16 v[118:121], v[130:133], v[166:169], v[118:121]
	v_mfma_f32_16x16x32_bf16 v[114:117], v[138:141], v[166:169], v[114:117]
	v_mfma_f32_16x16x32_bf16 v[110:113], v[130:133], v[178:181], v[110:113]
	v_mfma_f32_16x16x32_bf16 v[106:109], v[138:141], v[178:181], v[106:109]
	v_mfma_f32_16x16x32_bf16 v[102:105], v[130:133], v[182:185], v[102:105]
	v_mfma_f32_16x16x32_bf16 v[98:101], v[138:141], v[182:185], v[98:101]
	v_mfma_f32_16x16x32_bf16 v[126:129], v[134:137], v[170:173], v[126:129]
	v_mfma_f32_16x16x32_bf16 v[122:125], v[142:145], v[170:173], v[122:125]
	v_mfma_f32_16x16x32_bf16 v[118:121], v[134:137], v[174:177], v[118:121]
	v_mfma_f32_16x16x32_bf16 v[114:117], v[142:145], v[174:177], v[114:117]
	v_mfma_f32_16x16x32_bf16 v[110:113], v[134:137], v[186:189], v[110:113]
	v_mfma_f32_16x16x32_bf16 v[106:109], v[142:145], v[186:189], v[106:109]
	v_mfma_f32_16x16x32_bf16 v[102:105], v[134:137], v[190:193], v[102:105]
	v_mfma_f32_16x16x32_bf16 v[98:101], v[142:145], v[190:193], v[98:101]
	v_mfma_f32_16x16x32_bf16 v[94:97], v[146:149], v[162:165], v[94:97]
	v_mfma_f32_16x16x32_bf16 v[90:93], v[154:157], v[162:165], v[90:93]
	v_mfma_f32_16x16x32_bf16 v[86:89], v[146:149], v[166:169], v[86:89]
	v_mfma_f32_16x16x32_bf16 v[82:85], v[154:157], v[166:169], v[82:85]
	v_mfma_f32_16x16x32_bf16 v[78:81], v[146:149], v[178:181], v[78:81]
	v_mfma_f32_16x16x32_bf16 v[74:77], v[154:157], v[178:181], v[74:77]
	v_mfma_f32_16x16x32_bf16 v[70:73], v[146:149], v[182:185], v[70:73]
	v_mfma_f32_16x16x32_bf16 v[66:69], v[154:157], v[182:185], v[66:69]
	v_mfma_f32_16x16x32_bf16 v[94:97], v[150:153], v[170:173], v[94:97]
	v_mfma_f32_16x16x32_bf16 v[90:93], v[158:161], v[170:173], v[90:93]
	v_mfma_f32_16x16x32_bf16 v[86:89], v[150:153], v[174:177], v[86:89]
	v_mfma_f32_16x16x32_bf16 v[82:85], v[158:161], v[174:177], v[82:85]
	v_mfma_f32_16x16x32_bf16 v[78:81], v[150:153], v[186:189], v[78:81]
	v_mfma_f32_16x16x32_bf16 v[74:77], v[158:161], v[186:189], v[74:77]
	v_mfma_f32_16x16x32_bf16 v[70:73], v[150:153], v[190:193], v[70:73]
	v_mfma_f32_16x16x32_bf16 v[66:69], v[158:161], v[190:193], v[66:69]
	s_barrier
	s_setprio 0
	s_mov_b32 m0, s36
	s_addk_i32 s81, 0x80
	ds_read_b128 v[162:165], v219 offset:49152
	ds_read_b128 v[166:169], v219 offset:51200
	ds_read_b128 v[170:173], v220 offset:49152
	ds_read_b128 v[174:177], v220 offset:51200
	ds_read_b128 v[178:181], v219 offset:53248
	ds_read_b128 v[182:185], v219 offset:55296
	ds_read_b128 v[186:189], v220 offset:53248
	ds_read_b128 v[190:193], v220 offset:55296
	buffer_load_dwordx4 v233, s[4:7], s81 offen lds
	s_mov_b32 m0, s37
	s_nop 0
	buffer_load_dwordx4 v234, s[4:7], s81 offen lds
	s_add_i32 s81, s81, s80
	s_mov_b32 m0, s40
	s_nop 0
	buffer_load_dwordx4 v233, s[4:7], s81 offen lds
	s_mov_b32 m0, s41
	s_nop 0
	buffer_load_dwordx4 v234, s[4:7], s81 offen lds
	s_mov_b32 m0, s38
	s_nop 0
	buffer_load_dwordx4 v235, s[4:7], s79 offen lds
	s_mov_b32 m0, s39
	s_nop 0
	buffer_load_dwordx4 v236, s[4:7], s79 offen lds
	s_waitcnt vmcnt(8)
	s_waitcnt lgkmcnt(0)
	s_setprio 1
	s_barrier
	v_mfma_f32_16x16x32_bf16 v[62:65], v[130:133], v[162:165], v[62:65]
	v_mfma_f32_16x16x32_bf16 v[58:61], v[138:141], v[162:165], v[58:61]
	v_mfma_f32_16x16x32_bf16 v[54:57], v[130:133], v[166:169], v[54:57]
	v_mfma_f32_16x16x32_bf16 v[50:53], v[138:141], v[166:169], v[50:53]
	v_mfma_f32_16x16x32_bf16 v[46:49], v[130:133], v[178:181], v[46:49]
	v_mfma_f32_16x16x32_bf16 v[42:45], v[138:141], v[178:181], v[42:45]
	v_mfma_f32_16x16x32_bf16 v[38:41], v[130:133], v[182:185], v[38:41]
	v_mfma_f32_16x16x32_bf16 v[34:37], v[138:141], v[182:185], v[34:37]
	v_mfma_f32_16x16x32_bf16 v[62:65], v[134:137], v[170:173], v[62:65]
	v_mfma_f32_16x16x32_bf16 v[58:61], v[142:145], v[170:173], v[58:61]
	v_mfma_f32_16x16x32_bf16 v[54:57], v[134:137], v[174:177], v[54:57]
	v_mfma_f32_16x16x32_bf16 v[50:53], v[142:145], v[174:177], v[50:53]
	v_mfma_f32_16x16x32_bf16 v[46:49], v[134:137], v[186:189], v[46:49]
	v_mfma_f32_16x16x32_bf16 v[42:45], v[142:145], v[186:189], v[42:45]
	v_mfma_f32_16x16x32_bf16 v[38:41], v[134:137], v[190:193], v[38:41]
	v_mfma_f32_16x16x32_bf16 v[34:37], v[142:145], v[190:193], v[34:37]
	v_mfma_f32_16x16x32_bf16 v[30:33], v[146:149], v[162:165], v[30:33]
	v_mfma_f32_16x16x32_bf16 v[26:29], v[154:157], v[162:165], v[26:29]
	v_mfma_f32_16x16x32_bf16 v[22:25], v[146:149], v[166:169], v[22:25]
	v_mfma_f32_16x16x32_bf16 v[18:21], v[154:157], v[166:169], v[18:21]
	v_mfma_f32_16x16x32_bf16 v[14:17], v[146:149], v[178:181], v[14:17]
	v_mfma_f32_16x16x32_bf16 v[10:13], v[154:157], v[178:181], v[10:13]
	v_mfma_f32_16x16x32_bf16 v[6:9], v[146:149], v[182:185], v[6:9]
	v_mfma_f32_16x16x32_bf16 v[2:5], v[154:157], v[182:185], v[2:5]
	v_mfma_f32_16x16x32_bf16 v[30:33], v[150:153], v[170:173], v[30:33]
	v_mfma_f32_16x16x32_bf16 v[26:29], v[158:161], v[170:173], v[26:29]
	v_mfma_f32_16x16x32_bf16 v[22:25], v[150:153], v[174:177], v[22:25]
	v_mfma_f32_16x16x32_bf16 v[18:21], v[158:161], v[174:177], v[18:21]
	v_mfma_f32_16x16x32_bf16 v[14:17], v[150:153], v[186:189], v[14:17]
	v_mfma_f32_16x16x32_bf16 v[10:13], v[158:161], v[186:189], v[10:13]
	v_mfma_f32_16x16x32_bf16 v[6:9], v[150:153], v[190:193], v[6:9]
	v_mfma_f32_16x16x32_bf16 v[2:5], v[158:161], v[190:193], v[2:5]
	s_barrier
	s_setprio 0
	s_add_i32 s4, s78, 2
	s_addk_i32 s62, 0x100
	s_addk_i32 s61, 0x100
	s_cmp_ge_u32 s78, s63
	s_mov_b32 s78, s4
	s_cbranch_scc0 .LBB0_546
	s_and_b64 vcc, exec, s[12:13]
	s_cbranch_vccz .LBB0_549
	s_barrier

.LBB0_841:
	ds_read_b128 v[130:133], v240
	ds_read_b128 v[134:137], v241
	ds_read_b128 v[138:141], v242
	ds_read_b128 v[142:145], v243
	ds_read_b128 v[146:149], v244
	ds_read_b128 v[150:153], v245
	ds_read_b128 v[154:157], v246
	ds_read_b128 v[158:161], v247
	s_add_i32 s8, s42, s5
	s_add_i32 s19, s34, s5
	s_add_i32 s18, s8, 0x800
	s_addk_i32 s19, 0x800
	s_cmp_eq_u32 s5, 0
	s_cselect_b32 s20, s0, s18
	s_cselect_b32 s19, s1, s19
	s_add_i32 s18, s20, 0x80
	s_add_i32 s21, s8, 0x40780
	s_mov_b32 s8, s70
	s_mov_b32 m0, s52
	ds_read_b128 v[162:165], v248
	ds_read_b128 v[166:169], v248 offset:2048
	ds_read_b128 v[170:173], v249
	ds_read_b128 v[174:177], v249 offset:2048
	ds_read_b128 v[178:181], v248 offset:4096
	ds_read_b128 v[182:185], v248 offset:6144
	ds_read_b128 v[186:189], v249 offset:4096
	ds_read_b128 v[190:193], v249 offset:6144
	buffer_load_dwordx4 v1, s[8:11], s21 offen lds
	s_mov_b32 m0, s53
	s_nop 0
	buffer_load_dwordx4 v234, s[8:11], s21 offen lds
	s_waitcnt vmcnt(8)
	s_waitcnt lgkmcnt(0)
	s_setprio 1
	s_barrier
	v_mfma_f32_16x16x32_bf16 v[74:77], v[130:133], v[162:165], v[74:77]
	v_mfma_f32_16x16x32_bf16 v[70:73], v[138:141], v[162:165], v[70:73]
	v_mfma_f32_16x16x32_bf16 v[66:69], v[130:133], v[166:169], v[66:69]
	v_mfma_f32_16x16x32_bf16 v[82:85], v[138:141], v[166:169], v[82:85]
	v_mfma_f32_16x16x32_bf16 v[78:81], v[130:133], v[178:181], v[78:81]
	v_mfma_f32_16x16x32_bf16 v[90:93], v[138:141], v[178:181], v[90:93]
	v_mfma_f32_16x16x32_bf16 v[86:89], v[130:133], v[182:185], v[86:89]
	v_mfma_f32_16x16x32_bf16 v[102:105], v[138:141], v[182:185], v[102:105]
	v_mfma_f32_16x16x32_bf16 v[74:77], v[134:137], v[170:173], v[74:77]
	v_mfma_f32_16x16x32_bf16 v[70:73], v[142:145], v[170:173], v[70:73]
	v_mfma_f32_16x16x32_bf16 v[66:69], v[134:137], v[174:177], v[66:69]
	v_mfma_f32_16x16x32_bf16 v[82:85], v[142:145], v[174:177], v[82:85]
	v_mfma_f32_16x16x32_bf16 v[78:81], v[134:137], v[186:189], v[78:81]
	v_mfma_f32_16x16x32_bf16 v[90:93], v[142:145], v[186:189], v[90:93]
	v_mfma_f32_16x16x32_bf16 v[86:89], v[134:137], v[190:193], v[86:89]
	v_mfma_f32_16x16x32_bf16 v[102:105], v[142:145], v[190:193], v[102:105]
	v_mfma_f32_16x16x32_bf16 v[98:101], v[146:149], v[162:165], v[98:101]
	v_mfma_f32_16x16x32_bf16 v[94:97], v[154:157], v[162:165], v[94:97]
	v_mfma_f32_16x16x32_bf16 v[106:109], v[146:149], v[166:169], v[106:109]
	v_mfma_f32_16x16x32_bf16 v[110:113], v[154:157], v[166:169], v[110:113]
	v_mfma_f32_16x16x32_bf16 v[114:117], v[146:149], v[178:181], v[114:117]
	v_mfma_f32_16x16x32_bf16 v[118:121], v[154:157], v[178:181], v[118:121]
	v_mfma_f32_16x16x32_bf16 v[122:125], v[146:149], v[182:185], v[122:125]
	v_mfma_f32_16x16x32_bf16 v[126:129], v[154:157], v[182:185], v[126:129]
	v_mfma_f32_16x16x32_bf16 v[98:101], v[150:153], v[170:173], v[98:101]
	v_mfma_f32_16x16x32_bf16 v[94:97], v[158:161], v[170:173], v[94:97]
	v_mfma_f32_16x16x32_bf16 v[106:109], v[150:153], v[174:177], v[106:109]
	v_mfma_f32_16x16x32_bf16 v[110:113], v[158:161], v[174:177], v[110:113]
	v_mfma_f32_16x16x32_bf16 v[114:117], v[150:153], v[186:189], v[114:117]
	v_mfma_f32_16x16x32_bf16 v[118:121], v[158:161], v[186:189], v[118:121]
	v_mfma_f32_16x16x32_bf16 v[122:125], v[150:153], v[190:193], v[122:125]
	v_mfma_f32_16x16x32_bf16 v[126:129], v[158:161], v[190:193], v[126:129]
	s_barrier
	s_setprio 0
	s_mov_b32 m0, s29
	ds_read_b128 v[162:165], v248 offset:16384
	ds_read_b128 v[166:169], v248 offset:18432
	ds_read_b128 v[170:173], v249 offset:16384
	ds_read_b128 v[174:177], v249 offset:18432
	ds_read_b128 v[178:181], v248 offset:20480
	ds_read_b128 v[182:185], v248 offset:22528
	ds_read_b128 v[186:189], v249 offset:20480
	ds_read_b128 v[190:193], v249 offset:22528
	buffer_load_dwordx4 v233, s[8:11], s19 offen lds
	s_mov_b32 m0, s30
	s_add_i32 s21, s19, 0x40000
	buffer_load_dwordx4 v235, s[8:11], s19 offen lds
	s_mov_b32 m0, s31
	s_nop 0
	buffer_load_dwordx4 v233, s[8:11], s21 offen lds
	s_mov_b32 m0, s35
	s_nop 0
	buffer_load_dwordx4 v235, s[8:11], s21 offen lds
	s_mov_b32 m0, s28
	s_nop 0
	buffer_load_dwordx4 v1, s[8:11], s20 offen lds
	s_mov_b32 m0, s38
	s_nop 0
	buffer_load_dwordx4 v234, s[8:11], s20 offen lds
	s_waitcnt vmcnt(8)
	s_waitcnt lgkmcnt(0)
	s_setprio 1
	s_barrier
	v_mfma_f32_16x16x32_bf16 v[10:13], v[130:133], v[162:165], v[10:13]
	v_mfma_f32_16x16x32_bf16 v[6:9], v[138:141], v[162:165], v[6:9]
	v_mfma_f32_16x16x32_bf16 v[2:5], v[130:133], v[166:169], v[2:5]
	v_mfma_f32_16x16x32_bf16 v[18:21], v[138:141], v[166:169], v[18:21]
	v_mfma_f32_16x16x32_bf16 v[14:17], v[130:133], v[178:181], v[14:17]
	v_mfma_f32_16x16x32_bf16 v[26:29], v[138:141], v[178:181], v[26:29]
	v_mfma_f32_16x16x32_bf16 v[22:25], v[130:133], v[182:185], v[22:25]
	v_mfma_f32_16x16x32_bf16 v[38:41], v[138:141], v[182:185], v[38:41]
	v_mfma_f32_16x16x32_bf16 v[10:13], v[134:137], v[170:173], v[10:13]
	v_mfma_f32_16x16x32_bf16 v[6:9], v[142:145], v[170:173], v[6:9]
	v_mfma_f32_16x16x32_bf16 v[2:5], v[134:137], v[174:177], v[2:5]
	v_mfma_f32_16x16x32_bf16 v[18:21], v[142:145], v[174:177], v[18:21]
	v_mfma_f32_16x16x32_bf16 v[14:17], v[134:137], v[186:189], v[14:17]
	v_mfma_f32_16x16x32_bf16 v[26:29], v[142:145], v[186:189], v[26:29]
	v_mfma_f32_16x16x32_bf16 v[22:25], v[134:137], v[190:193], v[22:25]
	v_mfma_f32_16x16x32_bf16 v[38:41], v[142:145], v[190:193], v[38:41]
	v_mfma_f32_16x16x32_bf16 v[34:37], v[146:149], v[162:165], v[34:37]
	v_mfma_f32_16x16x32_bf16 v[30:33], v[154:157], v[162:165], v[30:33]
	v_mfma_f32_16x16x32_bf16 v[42:45], v[146:149], v[166:169], v[42:45]
	v_mfma_f32_16x16x32_bf16 v[46:49], v[154:157], v[166:169], v[46:49]
	v_mfma_f32_16x16x32_bf16 v[50:53], v[146:149], v[178:181], v[50:53]
	v_mfma_f32_16x16x32_bf16 v[54:57], v[154:157], v[178:181], v[54:57]
	v_mfma_f32_16x16x32_bf16 v[58:61], v[146:149], v[182:185], v[58:61]
	v_mfma_f32_16x16x32_bf16 v[62:65], v[154:157], v[182:185], v[62:65]
	v_mfma_f32_16x16x32_bf16 v[34:37], v[150:153], v[170:173], v[34:37]
	v_mfma_f32_16x16x32_bf16 v[30:33], v[158:161], v[170:173], v[30:33]
	v_mfma_f32_16x16x32_bf16 v[42:45], v[150:153], v[174:177], v[42:45]
	v_mfma_f32_16x16x32_bf16 v[46:49], v[158:161], v[174:177], v[46:49]
	v_mfma_f32_16x16x32_bf16 v[50:53], v[150:153], v[186:189], v[50:53]
	v_mfma_f32_16x16x32_bf16 v[54:57], v[158:161], v[186:189], v[54:57]
	v_mfma_f32_16x16x32_bf16 v[58:61], v[150:153], v[190:193], v[58:61]
	v_mfma_f32_16x16x32_bf16 v[62:65], v[158:161], v[190:193], v[62:65]
	s_barrier
	s_setprio 0
	ds_read_b128 v[130:133], v194
	ds_read_b128 v[134:137], v195
	ds_read_b128 v[138:141], v196
	ds_read_b128 v[142:145], v197
	ds_read_b128 v[146:149], v198
	ds_read_b128 v[150:153], v199
	ds_read_b128 v[154:157], v200
	ds_read_b128 v[158:161], v201
	s_add_i32 s20, s20, 0x40000
	s_mov_b32 m0, s39
	ds_read_b128 v[162:165], v248 offset:32768
	ds_read_b128 v[166:169], v248 offset:34816
	ds_read_b128 v[170:173], v249 offset:32768
	ds_read_b128 v[174:177], v249 offset:34816
	ds_read_b128 v[178:181], v248 offset:36864
	ds_read_b128 v[182:185], v248 offset:38912
	ds_read_b128 v[186:189], v249 offset:36864
	ds_read_b128 v[190:193], v249 offset:38912
	buffer_load_dwordx4 v1, s[8:11], s20 offen lds
	s_mov_b32 m0, s41
	s_nop 0
	buffer_load_dwordx4 v234, s[8:11], s20 offen lds
	s_waitcnt vmcnt(8)
	s_waitcnt lgkmcnt(0)
	s_setprio 1
	s_barrier
	v_mfma_f32_16x16x32_bf16 v[74:77], v[130:133], v[162:165], v[74:77]
	v_mfma_f32_16x16x32_bf16 v[70:73], v[138:141], v[162:165], v[70:73]
	v_mfma_f32_16x16x32_bf16 v[66:69], v[130:133], v[166:169], v[66:69]
	v_mfma_f32_16x16x32_bf16 v[82:85], v[138:141], v[166:169], v[82:85]
	v_mfma_f32_16x16x32_bf16 v[78:81], v[130:133], v[178:181], v[78:81]
	v_mfma_f32_16x16x32_bf16 v[90:93], v[138:141], v[178:181], v[90:93]
	v_mfma_f32_16x16x32_bf16 v[86:89], v[130:133], v[182:185], v[86:89]
	v_mfma_f32_16x16x32_bf16 v[102:105], v[138:141], v[182:185], v[102:105]
	v_mfma_f32_16x16x32_bf16 v[74:77], v[134:137], v[170:173], v[74:77]
	v_mfma_f32_16x16x32_bf16 v[70:73], v[142:145], v[170:173], v[70:73]
	v_mfma_f32_16x16x32_bf16 v[66:69], v[134:137], v[174:177], v[66:69]
	v_mfma_f32_16x16x32_bf16 v[82:85], v[142:145], v[174:177], v[82:85]
	v_mfma_f32_16x16x32_bf16 v[78:81], v[134:137], v[186:189], v[78:81]
	v_mfma_f32_16x16x32_bf16 v[90:93], v[142:145], v[186:189], v[90:93]
	v_mfma_f32_16x16x32_bf16 v[86:89], v[134:137], v[190:193], v[86:89]
	v_mfma_f32_16x16x32_bf16 v[102:105], v[142:145], v[190:193], v[102:105]
	v_mfma_f32_16x16x32_bf16 v[98:101], v[146:149], v[162:165], v[98:101]
	v_mfma_f32_16x16x32_bf16 v[94:97], v[154:157], v[162:165], v[94:97]
	v_mfma_f32_16x16x32_bf16 v[106:109], v[146:149], v[166:169], v[106:109]
	v_mfma_f32_16x16x32_bf16 v[110:113], v[154:157], v[166:169], v[110:113]
	v_mfma_f32_16x16x32_bf16 v[114:117], v[146:149], v[178:181], v[114:117]
	v_mfma_f32_16x16x32_bf16 v[118:121], v[154:157], v[178:181], v[118:121]
	v_mfma_f32_16x16x32_bf16 v[122:125], v[146:149], v[182:185], v[122:125]
	v_mfma_f32_16x16x32_bf16 v[126:129], v[154:157], v[182:185], v[126:129]
	v_mfma_f32_16x16x32_bf16 v[98:101], v[150:153], v[170:173], v[98:101]
	v_mfma_f32_16x16x32_bf16 v[94:97], v[158:161], v[170:173], v[94:97]
	v_mfma_f32_16x16x32_bf16 v[106:109], v[150:153], v[174:177], v[106:109]
	v_mfma_f32_16x16x32_bf16 v[110:113], v[158:161], v[174:177], v[110:113]
	v_mfma_f32_16x16x32_bf16 v[114:117], v[150:153], v[186:189], v[114:117]
	v_mfma_f32_16x16x32_bf16 v[118:121], v[158:161], v[186:189], v[118:121]
	v_mfma_f32_16x16x32_bf16 v[122:125], v[150:153], v[190:193], v[122:125]
	v_mfma_f32_16x16x32_bf16 v[126:129], v[158:161], v[190:193], v[126:129]
	s_barrier
	s_setprio 0
	s_mov_b32 m0, s44
	s_add_i32 s20, s19, 0x80
	ds_read_b128 v[162:165], v248 offset:49152
	ds_read_b128 v[166:169], v248 offset:51200
	ds_read_b128 v[170:173], v249 offset:49152
	ds_read_b128 v[174:177], v249 offset:51200
	ds_read_b128 v[178:181], v248 offset:53248
	ds_read_b128 v[182:185], v248 offset:55296
	ds_read_b128 v[186:189], v249 offset:53248
	ds_read_b128 v[190:193], v249 offset:55296
	buffer_load_dwordx4 v233, s[8:11], s20 offen lds
	s_mov_b32 m0, s45
	s_add_i32 s19, s19, 0x40080
	buffer_load_dwordx4 v235, s[8:11], s20 offen lds
	s_mov_b32 m0, s48
	s_nop 0
	buffer_load_dwordx4 v233, s[8:11], s19 offen lds
	s_mov_b32 m0, s49
	s_nop 0
	buffer_load_dwordx4 v235, s[8:11], s19 offen lds
	s_mov_b32 m0, s46
	s_nop 0
	buffer_load_dwordx4 v1, s[8:11], s18 offen lds
	s_mov_b32 m0, s47
	s_nop 0
	buffer_load_dwordx4 v234, s[8:11], s18 offen lds
	s_waitcnt vmcnt(8)
	s_waitcnt lgkmcnt(0)
	s_setprio 1
	s_barrier
	v_mfma_f32_16x16x32_bf16 v[10:13], v[130:133], v[162:165], v[10:13]
	v_mfma_f32_16x16x32_bf16 v[6:9], v[138:141], v[162:165], v[6:9]
	v_mfma_f32_16x16x32_bf16 v[2:5], v[130:133], v[166:169], v[2:5]
	v_mfma_f32_16x16x32_bf16 v[18:21], v[138:141], v[166:169], v[18:21]
	v_mfma_f32_16x16x32_bf16 v[14:17], v[130:133], v[178:181], v[14:17]
	v_mfma_f32_16x16x32_bf16 v[26:29], v[138:141], v[178:181], v[26:29]
	v_mfma_f32_16x16x32_bf16 v[22:25], v[130:133], v[182:185], v[22:25]
	v_mfma_f32_16x16x32_bf16 v[38:41], v[138:141], v[182:185], v[38:41]
	v_mfma_f32_16x16x32_bf16 v[10:13], v[134:137], v[170:173], v[10:13]
	v_mfma_f32_16x16x32_bf16 v[6:9], v[142:145], v[170:173], v[6:9]
	v_mfma_f32_16x16x32_bf16 v[2:5], v[134:137], v[174:177], v[2:5]
	v_mfma_f32_16x16x32_bf16 v[18:21], v[142:145], v[174:177], v[18:21]
	v_mfma_f32_16x16x32_bf16 v[14:17], v[134:137], v[186:189], v[14:17]
	v_mfma_f32_16x16x32_bf16 v[26:29], v[142:145], v[186:189], v[26:29]
	v_mfma_f32_16x16x32_bf16 v[22:25], v[134:137], v[190:193], v[22:25]
	v_mfma_f32_16x16x32_bf16 v[38:41], v[142:145], v[190:193], v[38:41]
	v_mfma_f32_16x16x32_bf16 v[34:37], v[146:149], v[162:165], v[34:37]
	v_mfma_f32_16x16x32_bf16 v[30:33], v[154:157], v[162:165], v[30:33]
	v_mfma_f32_16x16x32_bf16 v[42:45], v[146:149], v[166:169], v[42:45]
	v_mfma_f32_16x16x32_bf16 v[46:49], v[154:157], v[166:169], v[46:49]
	v_mfma_f32_16x16x32_bf16 v[50:53], v[146:149], v[178:181], v[50:53]
	v_mfma_f32_16x16x32_bf16 v[54:57], v[154:157], v[178:181], v[54:57]
	v_mfma_f32_16x16x32_bf16 v[58:61], v[146:149], v[182:185], v[58:61]
	v_mfma_f32_16x16x32_bf16 v[62:65], v[154:157], v[182:185], v[62:65]
	v_mfma_f32_16x16x32_bf16 v[34:37], v[150:153], v[170:173], v[34:37]
	v_mfma_f32_16x16x32_bf16 v[30:33], v[158:161], v[170:173], v[30:33]
	v_mfma_f32_16x16x32_bf16 v[42:45], v[150:153], v[174:177], v[42:45]
	v_mfma_f32_16x16x32_bf16 v[46:49], v[158:161], v[174:177], v[46:49]
	v_mfma_f32_16x16x32_bf16 v[50:53], v[150:153], v[186:189], v[50:53]
	v_mfma_f32_16x16x32_bf16 v[54:57], v[158:161], v[186:189], v[54:57]
	v_mfma_f32_16x16x32_bf16 v[58:61], v[150:153], v[190:193], v[58:61]
	v_mfma_f32_16x16x32_bf16 v[62:65], v[158:161], v[190:193], v[62:65]
	s_barrier
	s_setprio 0
	s_add_i32 s4, s4, 2
	s_addk_i32 s5, 0x100
	s_cmp_gt_u32 s4, 13
	s_cbranch_scc0 .LBB0_841
	s_and_b64 vcc, exec, s[16:17]
	s_cbranch_vccz .LBB0_844
	s_barrier

.LBB0_1122:
	ds_read_b128 v[130:133], v240
	ds_read_b128 v[134:137], v241
	ds_read_b128 v[138:141], v242
	ds_read_b128 v[142:145], v243
	ds_read_b128 v[146:149], v244
	ds_read_b128 v[150:153], v245
	ds_read_b128 v[154:157], v246
	ds_read_b128 v[158:161], v247
	s_add_i32 s8, s31, s53
	s_add_i32 s55, s26, s53
	s_add_i32 s54, s8, 0x800
	s_addk_i32 s55, 0x800
	s_cmp_eq_u32 s53, 0
	s_cselect_b32 s56, s4, s54
	s_cselect_b32 s55, s5, s55
	s_add_i32 s54, s56, 0x80
	s_add_i32 s57, s8, 0x40780
	s_mov_b32 s8, s70
	s_mov_b32 m0, s44
	ds_read_b128 v[162:165], v248
	ds_read_b128 v[166:169], v248 offset:2048
	ds_read_b128 v[170:173], v249
	ds_read_b128 v[174:177], v249 offset:2048
	ds_read_b128 v[178:181], v248 offset:4096
	ds_read_b128 v[182:185], v248 offset:6144
	ds_read_b128 v[186:189], v249 offset:4096
	ds_read_b128 v[190:193], v249 offset:6144
	buffer_load_dwordx4 v1, s[8:11], s57 offen lds
	s_mov_b32 m0, s45
	s_nop 0
	buffer_load_dwordx4 v234, s[8:11], s57 offen lds
	s_waitcnt vmcnt(8)
	s_waitcnt lgkmcnt(0)
	s_setprio 1
	s_barrier
	v_mfma_f32_16x16x32_bf16 v[126:129], v[130:133], v[162:165], v[126:129]
	v_mfma_f32_16x16x32_bf16 v[122:125], v[138:141], v[162:165], v[122:125]
	v_mfma_f32_16x16x32_bf16 v[118:121], v[130:133], v[166:169], v[118:121]
	v_mfma_f32_16x16x32_bf16 v[114:117], v[138:141], v[166:169], v[114:117]
	v_mfma_f32_16x16x32_bf16 v[110:113], v[130:133], v[178:181], v[110:113]
	v_mfma_f32_16x16x32_bf16 v[106:109], v[138:141], v[178:181], v[106:109]
	v_mfma_f32_16x16x32_bf16 v[102:105], v[130:133], v[182:185], v[102:105]
	v_mfma_f32_16x16x32_bf16 v[98:101], v[138:141], v[182:185], v[98:101]
	v_mfma_f32_16x16x32_bf16 v[126:129], v[134:137], v[170:173], v[126:129]
	v_mfma_f32_16x16x32_bf16 v[122:125], v[142:145], v[170:173], v[122:125]
	v_mfma_f32_16x16x32_bf16 v[118:121], v[134:137], v[174:177], v[118:121]
	v_mfma_f32_16x16x32_bf16 v[114:117], v[142:145], v[174:177], v[114:117]
	v_mfma_f32_16x16x32_bf16 v[110:113], v[134:137], v[186:189], v[110:113]
	v_mfma_f32_16x16x32_bf16 v[106:109], v[142:145], v[186:189], v[106:109]
	v_mfma_f32_16x16x32_bf16 v[102:105], v[134:137], v[190:193], v[102:105]
	v_mfma_f32_16x16x32_bf16 v[98:101], v[142:145], v[190:193], v[98:101]
	v_mfma_f32_16x16x32_bf16 v[94:97], v[146:149], v[162:165], v[94:97]
	v_mfma_f32_16x16x32_bf16 v[90:93], v[154:157], v[162:165], v[90:93]
	v_mfma_f32_16x16x32_bf16 v[86:89], v[146:149], v[166:169], v[86:89]
	v_mfma_f32_16x16x32_bf16 v[82:85], v[154:157], v[166:169], v[82:85]
	v_mfma_f32_16x16x32_bf16 v[78:81], v[146:149], v[178:181], v[78:81]
	v_mfma_f32_16x16x32_bf16 v[74:77], v[154:157], v[178:181], v[74:77]
	v_mfma_f32_16x16x32_bf16 v[70:73], v[146:149], v[182:185], v[70:73]
	v_mfma_f32_16x16x32_bf16 v[66:69], v[154:157], v[182:185], v[66:69]
	v_mfma_f32_16x16x32_bf16 v[94:97], v[150:153], v[170:173], v[94:97]
	v_mfma_f32_16x16x32_bf16 v[90:93], v[158:161], v[170:173], v[90:93]
	v_mfma_f32_16x16x32_bf16 v[86:89], v[150:153], v[174:177], v[86:89]
	v_mfma_f32_16x16x32_bf16 v[82:85], v[158:161], v[174:177], v[82:85]
	v_mfma_f32_16x16x32_bf16 v[78:81], v[150:153], v[186:189], v[78:81]
	v_mfma_f32_16x16x32_bf16 v[74:77], v[158:161], v[186:189], v[74:77]
	v_mfma_f32_16x16x32_bf16 v[70:73], v[150:153], v[190:193], v[70:73]
	v_mfma_f32_16x16x32_bf16 v[66:69], v[158:161], v[190:193], v[66:69]
	s_barrier
	s_setprio 0
	s_mov_b32 m0, s23
	ds_read_b128 v[162:165], v248 offset:16384
	ds_read_b128 v[166:169], v248 offset:18432
	ds_read_b128 v[170:173], v249 offset:16384
	ds_read_b128 v[174:177], v249 offset:18432
	ds_read_b128 v[178:181], v248 offset:20480
	ds_read_b128 v[182:185], v248 offset:22528
	ds_read_b128 v[186:189], v249 offset:20480
	ds_read_b128 v[190:193], v249 offset:22528
	buffer_load_dwordx4 v233, s[8:11], s55 offen lds
	s_mov_b32 m0, s24
	s_add_i32 s57, s55, 0x40000
	buffer_load_dwordx4 v235, s[8:11], s55 offen lds
	s_mov_b32 m0, s25
	s_nop 0
	buffer_load_dwordx4 v233, s[8:11], s57 offen lds
	s_mov_b32 m0, s27
	s_nop 0
	buffer_load_dwordx4 v235, s[8:11], s57 offen lds
	s_mov_b32 m0, s22
	s_nop 0
	buffer_load_dwordx4 v1, s[8:11], s56 offen lds
	s_mov_b32 m0, s28
	s_nop 0
	buffer_load_dwordx4 v234, s[8:11], s56 offen lds
	s_waitcnt vmcnt(8)
	s_waitcnt lgkmcnt(0)
	s_setprio 1
	s_barrier
	v_mfma_f32_16x16x32_bf16 v[62:65], v[130:133], v[162:165], v[62:65]
	v_mfma_f32_16x16x32_bf16 v[58:61], v[138:141], v[162:165], v[58:61]
	v_mfma_f32_16x16x32_bf16 v[54:57], v[130:133], v[166:169], v[54:57]
	v_mfma_f32_16x16x32_bf16 v[50:53], v[138:141], v[166:169], v[50:53]
	v_mfma_f32_16x16x32_bf16 v[46:49], v[130:133], v[178:181], v[46:49]
	v_mfma_f32_16x16x32_bf16 v[42:45], v[138:141], v[178:181], v[42:45]
	v_mfma_f32_16x16x32_bf16 v[38:41], v[130:133], v[182:185], v[38:41]
	v_mfma_f32_16x16x32_bf16 v[34:37], v[138:141], v[182:185], v[34:37]
	v_mfma_f32_16x16x32_bf16 v[62:65], v[134:137], v[170:173], v[62:65]
	v_mfma_f32_16x16x32_bf16 v[58:61], v[142:145], v[170:173], v[58:61]
	v_mfma_f32_16x16x32_bf16 v[54:57], v[134:137], v[174:177], v[54:57]
	v_mfma_f32_16x16x32_bf16 v[50:53], v[142:145], v[174:177], v[50:53]
	v_mfma_f32_16x16x32_bf16 v[46:49], v[134:137], v[186:189], v[46:49]
	v_mfma_f32_16x16x32_bf16 v[42:45], v[142:145], v[186:189], v[42:45]
	v_mfma_f32_16x16x32_bf16 v[38:41], v[134:137], v[190:193], v[38:41]
	v_mfma_f32_16x16x32_bf16 v[34:37], v[142:145], v[190:193], v[34:37]
	v_mfma_f32_16x16x32_bf16 v[30:33], v[146:149], v[162:165], v[30:33]
	v_mfma_f32_16x16x32_bf16 v[26:29], v[154:157], v[162:165], v[26:29]
	v_mfma_f32_16x16x32_bf16 v[22:25], v[146:149], v[166:169], v[22:25]
	v_mfma_f32_16x16x32_bf16 v[18:21], v[154:157], v[166:169], v[18:21]
	v_mfma_f32_16x16x32_bf16 v[14:17], v[146:149], v[178:181], v[14:17]
	v_mfma_f32_16x16x32_bf16 v[10:13], v[154:157], v[178:181], v[10:13]
	v_mfma_f32_16x16x32_bf16 v[6:9], v[146:149], v[182:185], v[6:9]
	v_mfma_f32_16x16x32_bf16 v[2:5], v[154:157], v[182:185], v[2:5]
	v_mfma_f32_16x16x32_bf16 v[30:33], v[150:153], v[170:173], v[30:33]
	v_mfma_f32_16x16x32_bf16 v[26:29], v[158:161], v[170:173], v[26:29]
	v_mfma_f32_16x16x32_bf16 v[22:25], v[150:153], v[174:177], v[22:25]
	v_mfma_f32_16x16x32_bf16 v[18:21], v[158:161], v[174:177], v[18:21]
	v_mfma_f32_16x16x32_bf16 v[14:17], v[150:153], v[186:189], v[14:17]
	v_mfma_f32_16x16x32_bf16 v[10:13], v[158:161], v[186:189], v[10:13]
	v_mfma_f32_16x16x32_bf16 v[6:9], v[150:153], v[190:193], v[6:9]
	v_mfma_f32_16x16x32_bf16 v[2:5], v[158:161], v[190:193], v[2:5]
	s_barrier
	s_setprio 0
	ds_read_b128 v[130:133], v194
	ds_read_b128 v[134:137], v195
	ds_read_b128 v[138:141], v196
	ds_read_b128 v[142:145], v197
	ds_read_b128 v[146:149], v198
	ds_read_b128 v[150:153], v199
	ds_read_b128 v[154:157], v200
	ds_read_b128 v[158:161], v201
	s_add_i32 s56, s56, 0x40000
	s_mov_b32 m0, s29
	ds_read_b128 v[162:165], v248 offset:32768
	ds_read_b128 v[166:169], v248 offset:34816
	ds_read_b128 v[170:173], v249 offset:32768
	ds_read_b128 v[174:177], v249 offset:34816
	ds_read_b128 v[178:181], v248 offset:36864
	ds_read_b128 v[182:185], v248 offset:38912
	ds_read_b128 v[186:189], v249 offset:36864
	ds_read_b128 v[190:193], v249 offset:38912
	buffer_load_dwordx4 v1, s[8:11], s56 offen lds
	s_mov_b32 m0, s30
	s_nop 0
	buffer_load_dwordx4 v234, s[8:11], s56 offen lds
	s_waitcnt vmcnt(8)
	s_waitcnt lgkmcnt(0)
	s_setprio 1
	s_barrier
	v_mfma_f32_16x16x32_bf16 v[126:129], v[130:133], v[162:165], v[126:129]
	v_mfma_f32_16x16x32_bf16 v[122:125], v[138:141], v[162:165], v[122:125]
	v_mfma_f32_16x16x32_bf16 v[118:121], v[130:133], v[166:169], v[118:121]
	v_mfma_f32_16x16x32_bf16 v[114:117], v[138:141], v[166:169], v[114:117]
	v_mfma_f32_16x16x32_bf16 v[110:113], v[130:133], v[178:181], v[110:113]
	v_mfma_f32_16x16x32_bf16 v[106:109], v[138:141], v[178:181], v[106:109]
	v_mfma_f32_16x16x32_bf16 v[102:105], v[130:133], v[182:185], v[102:105]
	v_mfma_f32_16x16x32_bf16 v[98:101], v[138:141], v[182:185], v[98:101]
	v_mfma_f32_16x16x32_bf16 v[126:129], v[134:137], v[170:173], v[126:129]
	v_mfma_f32_16x16x32_bf16 v[122:125], v[142:145], v[170:173], v[122:125]
	v_mfma_f32_16x16x32_bf16 v[118:121], v[134:137], v[174:177], v[118:121]
	v_mfma_f32_16x16x32_bf16 v[114:117], v[142:145], v[174:177], v[114:117]
	v_mfma_f32_16x16x32_bf16 v[110:113], v[134:137], v[186:189], v[110:113]
	v_mfma_f32_16x16x32_bf16 v[106:109], v[142:145], v[186:189], v[106:109]
	v_mfma_f32_16x16x32_bf16 v[102:105], v[134:137], v[190:193], v[102:105]
	v_mfma_f32_16x16x32_bf16 v[98:101], v[142:145], v[190:193], v[98:101]
	v_mfma_f32_16x16x32_bf16 v[94:97], v[146:149], v[162:165], v[94:97]
	v_mfma_f32_16x16x32_bf16 v[90:93], v[154:157], v[162:165], v[90:93]
	v_mfma_f32_16x16x32_bf16 v[86:89], v[146:149], v[166:169], v[86:89]
	v_mfma_f32_16x16x32_bf16 v[82:85], v[154:157], v[166:169], v[82:85]
	v_mfma_f32_16x16x32_bf16 v[78:81], v[146:149], v[178:181], v[78:81]
	v_mfma_f32_16x16x32_bf16 v[74:77], v[154:157], v[178:181], v[74:77]
	v_mfma_f32_16x16x32_bf16 v[70:73], v[146:149], v[182:185], v[70:73]
	v_mfma_f32_16x16x32_bf16 v[66:69], v[154:157], v[182:185], v[66:69]
	v_mfma_f32_16x16x32_bf16 v[94:97], v[150:153], v[170:173], v[94:97]
	v_mfma_f32_16x16x32_bf16 v[90:93], v[158:161], v[170:173], v[90:93]
	v_mfma_f32_16x16x32_bf16 v[86:89], v[150:153], v[174:177], v[86:89]
	v_mfma_f32_16x16x32_bf16 v[82:85], v[158:161], v[174:177], v[82:85]
	v_mfma_f32_16x16x32_bf16 v[78:81], v[150:153], v[186:189], v[78:81]
	v_mfma_f32_16x16x32_bf16 v[74:77], v[158:161], v[186:189], v[74:77]
	v_mfma_f32_16x16x32_bf16 v[70:73], v[150:153], v[190:193], v[70:73]
	v_mfma_f32_16x16x32_bf16 v[66:69], v[158:161], v[190:193], v[66:69]
	s_barrier
	s_setprio 0
	s_mov_b32 m0, s35
	s_add_i32 s56, s55, 0x80
	ds_read_b128 v[162:165], v248 offset:49152
	ds_read_b128 v[166:169], v248 offset:51200
	ds_read_b128 v[170:173], v249 offset:49152
	ds_read_b128 v[174:177], v249 offset:51200
	ds_read_b128 v[178:181], v248 offset:53248
	ds_read_b128 v[182:185], v248 offset:55296
	ds_read_b128 v[186:189], v249 offset:53248
	ds_read_b128 v[190:193], v249 offset:55296
	buffer_load_dwordx4 v233, s[8:11], s56 offen lds
	s_mov_b32 m0, s36
	s_add_i32 s55, s55, 0x40080
	buffer_load_dwordx4 v235, s[8:11], s56 offen lds
	s_mov_b32 m0, s39
	s_nop 0
	buffer_load_dwordx4 v233, s[8:11], s55 offen lds
	s_mov_b32 m0, s41
	s_nop 0
	buffer_load_dwordx4 v235, s[8:11], s55 offen lds
	s_mov_b32 m0, s37
	s_nop 0
	buffer_load_dwordx4 v1, s[8:11], s54 offen lds
	s_mov_b32 m0, s38
	s_nop 0
	buffer_load_dwordx4 v234, s[8:11], s54 offen lds
	s_waitcnt vmcnt(8)
	s_waitcnt lgkmcnt(0)
	s_setprio 1
	s_barrier
	v_mfma_f32_16x16x32_bf16 v[62:65], v[130:133], v[162:165], v[62:65]
	v_mfma_f32_16x16x32_bf16 v[58:61], v[138:141], v[162:165], v[58:61]
	v_mfma_f32_16x16x32_bf16 v[54:57], v[130:133], v[166:169], v[54:57]
	v_mfma_f32_16x16x32_bf16 v[50:53], v[138:141], v[166:169], v[50:53]
	v_mfma_f32_16x16x32_bf16 v[46:49], v[130:133], v[178:181], v[46:49]
	v_mfma_f32_16x16x32_bf16 v[42:45], v[138:141], v[178:181], v[42:45]
	v_mfma_f32_16x16x32_bf16 v[38:41], v[130:133], v[182:185], v[38:41]
	v_mfma_f32_16x16x32_bf16 v[34:37], v[138:141], v[182:185], v[34:37]
	v_mfma_f32_16x16x32_bf16 v[62:65], v[134:137], v[170:173], v[62:65]
	v_mfma_f32_16x16x32_bf16 v[58:61], v[142:145], v[170:173], v[58:61]
	v_mfma_f32_16x16x32_bf16 v[54:57], v[134:137], v[174:177], v[54:57]
	v_mfma_f32_16x16x32_bf16 v[50:53], v[142:145], v[174:177], v[50:53]
	v_mfma_f32_16x16x32_bf16 v[46:49], v[134:137], v[186:189], v[46:49]
	v_mfma_f32_16x16x32_bf16 v[42:45], v[142:145], v[186:189], v[42:45]
	v_mfma_f32_16x16x32_bf16 v[38:41], v[134:137], v[190:193], v[38:41]
	v_mfma_f32_16x16x32_bf16 v[34:37], v[142:145], v[190:193], v[34:37]
	v_mfma_f32_16x16x32_bf16 v[30:33], v[146:149], v[162:165], v[30:33]
	v_mfma_f32_16x16x32_bf16 v[26:29], v[154:157], v[162:165], v[26:29]
	v_mfma_f32_16x16x32_bf16 v[22:25], v[146:149], v[166:169], v[22:25]
	v_mfma_f32_16x16x32_bf16 v[18:21], v[154:157], v[166:169], v[18:21]
	v_mfma_f32_16x16x32_bf16 v[14:17], v[146:149], v[178:181], v[14:17]
	v_mfma_f32_16x16x32_bf16 v[10:13], v[154:157], v[178:181], v[10:13]
	v_mfma_f32_16x16x32_bf16 v[6:9], v[146:149], v[182:185], v[6:9]
	v_mfma_f32_16x16x32_bf16 v[2:5], v[154:157], v[182:185], v[2:5]
	v_mfma_f32_16x16x32_bf16 v[30:33], v[150:153], v[170:173], v[30:33]
	v_mfma_f32_16x16x32_bf16 v[26:29], v[158:161], v[170:173], v[26:29]
	v_mfma_f32_16x16x32_bf16 v[22:25], v[150:153], v[174:177], v[22:25]
	v_mfma_f32_16x16x32_bf16 v[18:21], v[158:161], v[174:177], v[18:21]
	v_mfma_f32_16x16x32_bf16 v[14:17], v[150:153], v[186:189], v[14:17]
	v_mfma_f32_16x16x32_bf16 v[10:13], v[158:161], v[186:189], v[10:13]
	v_mfma_f32_16x16x32_bf16 v[6:9], v[150:153], v[190:193], v[6:9]
	v_mfma_f32_16x16x32_bf16 v[2:5], v[158:161], v[190:193], v[2:5]
	s_barrier
	s_setprio 0
	s_add_i32 s33, s33, 2
	s_addk_i32 s53, 0x100
	s_cmp_gt_u32 s33, 13
	s_cbranch_scc0 .LBB0_1122
	s_and_b64 vcc, exec, s[16:17]
	s_cbranch_vccz .LBB0_1125
	s_barrier

.LBB0_1251:
	ds_read_b128 v[130:133], v239
	ds_read_b128 v[134:137], v240
	ds_read_b128 v[138:141], v241
	ds_read_b128 v[142:145], v242
	ds_read_b128 v[146:149], v243
	ds_read_b128 v[150:153], v244
	ds_read_b128 v[154:157], v245
	ds_read_b128 v[158:161], v246
	s_add_i32 s8, s51, s5
	s_add_i32 s31, s46, s5
	s_add_i32 s30, s8, 0x2000
	s_addk_i32 s31, 0x2000
	s_cmp_eq_u32 s5, 0
	s_cselect_b32 s33, s0, s30
	s_cselect_b32 s31, s1, s31
	s_add_i32 s30, s33, 0x80
	s_add_i32 s34, s8, 0x101f80
	s_mov_b32 s8, s70
	s_mov_b32 m0, s61
	ds_read_b128 v[162:165], v247
	ds_read_b128 v[166:169], v247 offset:2048
	ds_read_b128 v[170:173], v248
	ds_read_b128 v[174:177], v248 offset:2048
	ds_read_b128 v[178:181], v247 offset:4096
	ds_read_b128 v[182:185], v247 offset:6144
	ds_read_b128 v[186:189], v248 offset:4096
	ds_read_b128 v[190:193], v248 offset:6144
	buffer_load_dwordx4 v230, s[8:11], s34 offen lds
	s_mov_b32 m0, s64
	s_nop 0
	buffer_load_dwordx4 v233, s[8:11], s34 offen lds
	s_waitcnt vmcnt(8)
	s_waitcnt lgkmcnt(0)
	s_setprio 1
	s_barrier
	v_mfma_f32_16x16x32_bf16 v[74:77], v[130:133], v[162:165], v[74:77]
	v_mfma_f32_16x16x32_bf16 v[70:73], v[138:141], v[162:165], v[70:73]
	v_mfma_f32_16x16x32_bf16 v[66:69], v[130:133], v[166:169], v[66:69]
	v_mfma_f32_16x16x32_bf16 v[82:85], v[138:141], v[166:169], v[82:85]
	v_mfma_f32_16x16x32_bf16 v[78:81], v[130:133], v[178:181], v[78:81]
	v_mfma_f32_16x16x32_bf16 v[90:93], v[138:141], v[178:181], v[90:93]
	v_mfma_f32_16x16x32_bf16 v[86:89], v[130:133], v[182:185], v[86:89]
	v_mfma_f32_16x16x32_bf16 v[102:105], v[138:141], v[182:185], v[102:105]
	v_mfma_f32_16x16x32_bf16 v[74:77], v[134:137], v[170:173], v[74:77]
	v_mfma_f32_16x16x32_bf16 v[70:73], v[142:145], v[170:173], v[70:73]
	v_mfma_f32_16x16x32_bf16 v[66:69], v[134:137], v[174:177], v[66:69]
	v_mfma_f32_16x16x32_bf16 v[82:85], v[142:145], v[174:177], v[82:85]
	v_mfma_f32_16x16x32_bf16 v[78:81], v[134:137], v[186:189], v[78:81]
	v_mfma_f32_16x16x32_bf16 v[90:93], v[142:145], v[186:189], v[90:93]
	v_mfma_f32_16x16x32_bf16 v[86:89], v[134:137], v[190:193], v[86:89]
	v_mfma_f32_16x16x32_bf16 v[102:105], v[142:145], v[190:193], v[102:105]
	v_mfma_f32_16x16x32_bf16 v[98:101], v[146:149], v[162:165], v[98:101]
	v_mfma_f32_16x16x32_bf16 v[94:97], v[154:157], v[162:165], v[94:97]
	v_mfma_f32_16x16x32_bf16 v[106:109], v[146:149], v[166:169], v[106:109]
	v_mfma_f32_16x16x32_bf16 v[110:113], v[154:157], v[166:169], v[110:113]
	v_mfma_f32_16x16x32_bf16 v[114:117], v[146:149], v[178:181], v[114:117]
	v_mfma_f32_16x16x32_bf16 v[118:121], v[154:157], v[178:181], v[118:121]
	v_mfma_f32_16x16x32_bf16 v[122:125], v[146:149], v[182:185], v[122:125]
	v_mfma_f32_16x16x32_bf16 v[126:129], v[154:157], v[182:185], v[126:129]
	v_mfma_f32_16x16x32_bf16 v[98:101], v[150:153], v[170:173], v[98:101]
	v_mfma_f32_16x16x32_bf16 v[94:97], v[158:161], v[170:173], v[94:97]
	v_mfma_f32_16x16x32_bf16 v[106:109], v[150:153], v[174:177], v[106:109]
	v_mfma_f32_16x16x32_bf16 v[110:113], v[158:161], v[174:177], v[110:113]
	v_mfma_f32_16x16x32_bf16 v[114:117], v[150:153], v[186:189], v[114:117]
	v_mfma_f32_16x16x32_bf16 v[118:121], v[158:161], v[186:189], v[118:121]
	v_mfma_f32_16x16x32_bf16 v[122:125], v[150:153], v[190:193], v[122:125]
	v_mfma_f32_16x16x32_bf16 v[126:129], v[158:161], v[190:193], v[126:129]
	s_barrier
	s_setprio 0
	s_mov_b32 m0, s43
	ds_read_b128 v[162:165], v247 offset:16384
	ds_read_b128 v[166:169], v247 offset:18432
	ds_read_b128 v[170:173], v248 offset:16384
	ds_read_b128 v[174:177], v248 offset:18432
	ds_read_b128 v[178:181], v247 offset:20480
	ds_read_b128 v[182:185], v247 offset:22528
	ds_read_b128 v[186:189], v248 offset:20480
	ds_read_b128 v[190:193], v248 offset:22528
	buffer_load_dwordx4 v231, s[8:11], s31 offen lds
	s_mov_b32 m0, s44
	s_add_i32 s34, s31, 0x100000
	buffer_load_dwordx4 v234, s[8:11], s31 offen lds
	s_mov_b32 m0, s45
	s_nop 0
	buffer_load_dwordx4 v231, s[8:11], s34 offen lds
	s_mov_b32 m0, s47
	s_nop 0
	buffer_load_dwordx4 v234, s[8:11], s34 offen lds
	s_mov_b32 m0, s42
	s_nop 0
	buffer_load_dwordx4 v230, s[8:11], s33 offen lds
	s_mov_b32 m0, s48
	s_nop 0
	buffer_load_dwordx4 v233, s[8:11], s33 offen lds
	s_waitcnt vmcnt(8)
	s_waitcnt lgkmcnt(0)
	s_setprio 1
	s_barrier
	v_mfma_f32_16x16x32_bf16 v[10:13], v[130:133], v[162:165], v[10:13]
	v_mfma_f32_16x16x32_bf16 v[6:9], v[138:141], v[162:165], v[6:9]
	v_mfma_f32_16x16x32_bf16 v[0:3], v[130:133], v[166:169], v[2:5]
	v_mfma_f32_16x16x32_bf16 v[18:21], v[138:141], v[166:169], v[18:21]
	v_mfma_f32_16x16x32_bf16 v[14:17], v[130:133], v[178:181], v[14:17]
	v_mfma_f32_16x16x32_bf16 v[26:29], v[138:141], v[178:181], v[26:29]
	v_mfma_f32_16x16x32_bf16 v[22:25], v[130:133], v[182:185], v[22:25]
	v_mfma_f32_16x16x32_bf16 v[38:41], v[138:141], v[182:185], v[38:41]
	v_mfma_f32_16x16x32_bf16 v[10:13], v[134:137], v[170:173], v[10:13]
	v_mfma_f32_16x16x32_bf16 v[6:9], v[142:145], v[170:173], v[6:9]
	v_mfma_f32_16x16x32_bf16 v[0:3], v[134:137], v[174:177], v[0:3]
	v_mfma_f32_16x16x32_bf16 v[18:21], v[142:145], v[174:177], v[18:21]
	v_mfma_f32_16x16x32_bf16 v[14:17], v[134:137], v[186:189], v[14:17]
	v_mfma_f32_16x16x32_bf16 v[26:29], v[142:145], v[186:189], v[26:29]
	v_mfma_f32_16x16x32_bf16 v[22:25], v[134:137], v[190:193], v[22:25]
	v_mfma_f32_16x16x32_bf16 v[38:41], v[142:145], v[190:193], v[38:41]
	v_mfma_f32_16x16x32_bf16 v[34:37], v[146:149], v[162:165], v[34:37]
	v_mfma_f32_16x16x32_bf16 v[30:33], v[154:157], v[162:165], v[30:33]
	v_mfma_f32_16x16x32_bf16 v[42:45], v[146:149], v[166:169], v[42:45]
	v_mfma_f32_16x16x32_bf16 v[46:49], v[154:157], v[166:169], v[46:49]
	v_mfma_f32_16x16x32_bf16 v[50:53], v[146:149], v[178:181], v[50:53]
	v_mfma_f32_16x16x32_bf16 v[54:57], v[154:157], v[178:181], v[54:57]
	v_mfma_f32_16x16x32_bf16 v[58:61], v[146:149], v[182:185], v[58:61]
	v_mfma_f32_16x16x32_bf16 v[62:65], v[154:157], v[182:185], v[62:65]
	v_mfma_f32_16x16x32_bf16 v[34:37], v[150:153], v[170:173], v[34:37]
	v_mfma_f32_16x16x32_bf16 v[30:33], v[158:161], v[170:173], v[30:33]
	v_mfma_f32_16x16x32_bf16 v[42:45], v[150:153], v[174:177], v[42:45]
	v_mfma_f32_16x16x32_bf16 v[46:49], v[158:161], v[174:177], v[46:49]
	v_mfma_f32_16x16x32_bf16 v[50:53], v[150:153], v[186:189], v[50:53]
	v_mfma_f32_16x16x32_bf16 v[54:57], v[158:161], v[186:189], v[54:57]
	v_mfma_f32_16x16x32_bf16 v[58:61], v[150:153], v[190:193], v[58:61]
	v_mfma_f32_16x16x32_bf16 v[62:65], v[158:161], v[190:193], v[62:65]
	s_barrier
	s_setprio 0
	ds_read_b128 v[130:133], v194
	ds_read_b128 v[134:137], v195
	ds_read_b128 v[138:141], v196
	ds_read_b128 v[142:145], v197
	ds_read_b128 v[146:149], v198
	ds_read_b128 v[150:153], v199
	ds_read_b128 v[154:157], v200
	ds_read_b128 v[158:161], v201
	s_add_i32 s33, s33, 0x100000
	s_mov_b32 m0, s49
	ds_read_b128 v[162:165], v247 offset:32768
	ds_read_b128 v[166:169], v247 offset:34816
	ds_read_b128 v[170:173], v248 offset:32768
	ds_read_b128 v[174:177], v248 offset:34816
	ds_read_b128 v[178:181], v247 offset:36864
	ds_read_b128 v[182:185], v247 offset:38912
	ds_read_b128 v[186:189], v248 offset:36864
	ds_read_b128 v[190:193], v248 offset:38912
	buffer_load_dwordx4 v230, s[8:11], s33 offen lds
	s_mov_b32 m0, s50
	s_nop 0
	buffer_load_dwordx4 v233, s[8:11], s33 offen lds
	s_waitcnt vmcnt(8)
	s_waitcnt lgkmcnt(0)
	s_setprio 1
	s_barrier
	v_mfma_f32_16x16x32_bf16 v[74:77], v[130:133], v[162:165], v[74:77]
	v_mfma_f32_16x16x32_bf16 v[70:73], v[138:141], v[162:165], v[70:73]
	v_mfma_f32_16x16x32_bf16 v[66:69], v[130:133], v[166:169], v[66:69]
	v_mfma_f32_16x16x32_bf16 v[82:85], v[138:141], v[166:169], v[82:85]
	v_mfma_f32_16x16x32_bf16 v[78:81], v[130:133], v[178:181], v[78:81]
	v_mfma_f32_16x16x32_bf16 v[90:93], v[138:141], v[178:181], v[90:93]
	v_mfma_f32_16x16x32_bf16 v[86:89], v[130:133], v[182:185], v[86:89]
	v_mfma_f32_16x16x32_bf16 v[102:105], v[138:141], v[182:185], v[102:105]
	v_mfma_f32_16x16x32_bf16 v[74:77], v[134:137], v[170:173], v[74:77]
	v_mfma_f32_16x16x32_bf16 v[70:73], v[142:145], v[170:173], v[70:73]
	v_mfma_f32_16x16x32_bf16 v[66:69], v[134:137], v[174:177], v[66:69]
	v_mfma_f32_16x16x32_bf16 v[82:85], v[142:145], v[174:177], v[82:85]
	v_mfma_f32_16x16x32_bf16 v[78:81], v[134:137], v[186:189], v[78:81]
	v_mfma_f32_16x16x32_bf16 v[90:93], v[142:145], v[186:189], v[90:93]
	v_mfma_f32_16x16x32_bf16 v[86:89], v[134:137], v[190:193], v[86:89]
	v_mfma_f32_16x16x32_bf16 v[102:105], v[142:145], v[190:193], v[102:105]
	v_mfma_f32_16x16x32_bf16 v[98:101], v[146:149], v[162:165], v[98:101]
	v_mfma_f32_16x16x32_bf16 v[94:97], v[154:157], v[162:165], v[94:97]
	v_mfma_f32_16x16x32_bf16 v[106:109], v[146:149], v[166:169], v[106:109]
	v_mfma_f32_16x16x32_bf16 v[110:113], v[154:157], v[166:169], v[110:113]
	v_mfma_f32_16x16x32_bf16 v[114:117], v[146:149], v[178:181], v[114:117]
	v_mfma_f32_16x16x32_bf16 v[118:121], v[154:157], v[178:181], v[118:121]
	v_mfma_f32_16x16x32_bf16 v[122:125], v[146:149], v[182:185], v[122:125]
	v_mfma_f32_16x16x32_bf16 v[126:129], v[154:157], v[182:185], v[126:129]
	v_mfma_f32_16x16x32_bf16 v[98:101], v[150:153], v[170:173], v[98:101]
	v_mfma_f32_16x16x32_bf16 v[94:97], v[158:161], v[170:173], v[94:97]
	v_mfma_f32_16x16x32_bf16 v[106:109], v[150:153], v[174:177], v[106:109]
	v_mfma_f32_16x16x32_bf16 v[110:113], v[158:161], v[174:177], v[110:113]
	v_mfma_f32_16x16x32_bf16 v[114:117], v[150:153], v[186:189], v[114:117]
	v_mfma_f32_16x16x32_bf16 v[118:121], v[158:161], v[186:189], v[118:121]
	v_mfma_f32_16x16x32_bf16 v[122:125], v[150:153], v[190:193], v[122:125]
	v_mfma_f32_16x16x32_bf16 v[126:129], v[158:161], v[190:193], v[126:129]
	s_barrier
	s_setprio 0
	s_mov_b32 m0, s53
	s_add_i32 s33, s31, 0x80
	ds_read_b128 v[162:165], v247 offset:49152
	ds_read_b128 v[166:169], v247 offset:51200
	ds_read_b128 v[170:173], v248 offset:49152
	ds_read_b128 v[174:177], v248 offset:51200
	ds_read_b128 v[178:181], v247 offset:53248
	ds_read_b128 v[182:185], v247 offset:55296
	ds_read_b128 v[186:189], v248 offset:53248
	ds_read_b128 v[190:193], v248 offset:55296
	buffer_load_dwordx4 v231, s[8:11], s33 offen lds
	s_mov_b32 m0, s54
	s_add_i32 s31, s31, 0x100080
	buffer_load_dwordx4 v234, s[8:11], s33 offen lds
	s_mov_b32 m0, s57
	s_nop 0
	buffer_load_dwordx4 v231, s[8:11], s31 offen lds
	s_mov_b32 m0, s58
	s_nop 0
	buffer_load_dwordx4 v234, s[8:11], s31 offen lds
	s_mov_b32 m0, s55
	s_nop 0
	buffer_load_dwordx4 v230, s[8:11], s30 offen lds
	s_mov_b32 m0, s56
	s_nop 0
	buffer_load_dwordx4 v233, s[8:11], s30 offen lds
	s_waitcnt vmcnt(8)
	s_waitcnt lgkmcnt(0)
	s_setprio 1
	s_barrier
	v_mfma_f32_16x16x32_bf16 v[10:13], v[130:133], v[162:165], v[10:13]
	v_mfma_f32_16x16x32_bf16 v[4:7], v[138:141], v[162:165], v[6:9]
	v_mfma_f32_16x16x32_bf16 v[0:3], v[130:133], v[166:169], v[0:3]
	v_mfma_f32_16x16x32_bf16 v[18:21], v[138:141], v[166:169], v[18:21]
	v_mfma_f32_16x16x32_bf16 v[14:17], v[130:133], v[178:181], v[14:17]
	v_mfma_f32_16x16x32_bf16 v[26:29], v[138:141], v[178:181], v[26:29]
	v_mfma_f32_16x16x32_bf16 v[22:25], v[130:133], v[182:185], v[22:25]
	v_mfma_f32_16x16x32_bf16 v[38:41], v[138:141], v[182:185], v[38:41]
	v_mfma_f32_16x16x32_bf16 v[10:13], v[134:137], v[170:173], v[10:13]
	v_mfma_f32_16x16x32_bf16 v[6:9], v[142:145], v[170:173], v[4:7]
	v_mfma_f32_16x16x32_bf16 v[2:5], v[134:137], v[174:177], v[0:3]
	v_mfma_f32_16x16x32_bf16 v[18:21], v[142:145], v[174:177], v[18:21]
	v_mfma_f32_16x16x32_bf16 v[14:17], v[134:137], v[186:189], v[14:17]
	v_mfma_f32_16x16x32_bf16 v[26:29], v[142:145], v[186:189], v[26:29]
	v_mfma_f32_16x16x32_bf16 v[22:25], v[134:137], v[190:193], v[22:25]
	v_mfma_f32_16x16x32_bf16 v[38:41], v[142:145], v[190:193], v[38:41]
	v_mfma_f32_16x16x32_bf16 v[34:37], v[146:149], v[162:165], v[34:37]
	v_mfma_f32_16x16x32_bf16 v[30:33], v[154:157], v[162:165], v[30:33]
	v_mfma_f32_16x16x32_bf16 v[42:45], v[146:149], v[166:169], v[42:45]
	v_mfma_f32_16x16x32_bf16 v[46:49], v[154:157], v[166:169], v[46:49]
	v_mfma_f32_16x16x32_bf16 v[50:53], v[146:149], v[178:181], v[50:53]
	v_mfma_f32_16x16x32_bf16 v[54:57], v[154:157], v[178:181], v[54:57]
	v_mfma_f32_16x16x32_bf16 v[58:61], v[146:149], v[182:185], v[58:61]
	v_mfma_f32_16x16x32_bf16 v[62:65], v[154:157], v[182:185], v[62:65]
	v_mfma_f32_16x16x32_bf16 v[34:37], v[150:153], v[170:173], v[34:37]
	v_mfma_f32_16x16x32_bf16 v[30:33], v[158:161], v[170:173], v[30:33]
	v_mfma_f32_16x16x32_bf16 v[42:45], v[150:153], v[174:177], v[42:45]
	v_mfma_f32_16x16x32_bf16 v[46:49], v[158:161], v[174:177], v[46:49]
	v_mfma_f32_16x16x32_bf16 v[50:53], v[150:153], v[186:189], v[50:53]
	v_mfma_f32_16x16x32_bf16 v[54:57], v[158:161], v[186:189], v[54:57]
	v_mfma_f32_16x16x32_bf16 v[58:61], v[150:153], v[190:193], v[58:61]
	v_mfma_f32_16x16x32_bf16 v[62:65], v[158:161], v[190:193], v[62:65]
	s_barrier
	s_setprio 0
	s_add_i32 s4, s4, 2
	s_addk_i32 s5, 0x100
	s_cmp_gt_u32 s4, 61
	s_cbranch_scc0 .LBB0_1251
	s_and_b64 vcc, exec, s[18:19]
	s_cbranch_vccz .LBB0_1254
	s_barrier
